# v25: fused final norm + seam-7 skip + hand-written w_o and down-GEMM epilogues (without the SSD pass-3 XCC remap)
# baseline (speedup 1.0000x reference)
; __device__ __forceinline__ u32x4 pack8(const f32x4 a, const f32x4 b) { u32x4 w; w.x = cvt_pk_bf16(a[0], a[1]); w.y = cvt_pk_bf16(a[2], a[3]); w.z = cvt_pk_bf16(b[0], b[1]); w.w = cvt_pk_bf16(b[2], b[3]); return w; }
;     __device__ __forceinline__ void operator()(const f32x4 (&acc)[2][2][4][2], const pg8::Unit& u, int wr, int wc, int fr, int fq) const {
;         const int row0 = u.pm * 256 + wr * 64 + fr, col0 = u.pn * 256 + wc * 32 + 8 * fq;
; #pragma unroll
;         for (int ai = 0; ai < 2; ++ai) {
;             u32x4 hr[4][2]; float q1v[4];
; #pragma unroll
;             for (int m = 0; m < 4; ++m) { q1v[m] = rss1[row0 + ai * 128 + m * 16];
; #pragma unroll
;                 for (int bj = 0; bj < 2; ++bj) hr[m][bj] = *(const u32x4*)(HB + (size_t)(row0 + ai * 128 + m * 16) * DM + col0 + bj * 128); }
; #pragma unroll
;             for (int m = 0; m < 4; ++m) { const float iq = (127.f / QCLIP) * rsqrtf(q1v[m] * (1.f / DM) + EPS);
; #pragma unroll
;                 for (int bj = 0; bj < 2; ++bj) { float hv[8]; unpack8(hr[m][bj], hv); const size_t off = (size_t)(row0 + ai * 128 + m * 16) * DM + col0 + bj * 128;
;                     f32x4 h0 = acc[ai][bj][m][0], h1 = acc[ai][bj][m][1];
; #pragma unroll
;                     for (int e = 0; e < 4; ++e) { h0[e] += hv[e]; h1[e] += hv[4 + e]; }
;                     *(u32x4*)(HB + off) = pack8(h0, h1);
;                     f32x4 q0, q1;
; #pragma unroll
;                     for (int ee = 0; ee < 4; ++ee) { q0[ee] = fminf(fmaxf(rintf(h0[ee] * iq), -127.f), 127.f); q1[ee] = fminf(fmaxf(rintf(h1[ee] * iq), -127.f), 127.f); }
;                     *(u32x2*)(HQ + off) = pack8_i8(q0, q1); } }
.LBB0_1379:
	s_mov_b32 s98, s1
	s_mov_b32 s99, s4
	v_lshlrev_b32_e32 v162, 2, v1
	v_lshlrev_b32_e32 v163, 13, v1
	v_lshlrev_b32_e32 v164, 12, v1
	v_lshl_add_u32 v163, v181, 1, v163
	v_add_u32_e32 v164, v164, v181
	s_lshl_b32 s26, s98, 10
	s_add_u32 s28, s18, s26
	s_addc_u32 s29, s19, 0
	s_lshl_b32 s26, s98, 21
	s_lshl_b32 s27, s99, 9
	s_add_u32 s26, s26, s27
	s_add_u32 s84, s14, s26
	s_addc_u32 s85, s15, 0
	s_mov_b64 s[86:87], s[84:85]
	s_lshr_b32 s27, s26, 1
	s_add_u32 s88, s16, s27
	s_addc_u32 s89, s17, 0
	global_load_dword v165, v162, s[28:29]
	global_load_dwordx4 v[188:191], v163, s[84:85]
	global_load_dwordx4 v[192:195], v163, s[84:85] offset:256
	s_add_u32 s84, s84, 0x20000
	s_addc_u32 s85, s85, 0
	global_load_dword v166, v162, s[28:29] offset:64
	global_load_dwordx4 v[196:199], v163, s[84:85]
	global_load_dwordx4 v[200:203], v163, s[84:85] offset:256
	s_add_u32 s84, s84, 0x20000
	s_addc_u32 s85, s85, 0
	s_waitcnt vmcnt(3)
	v_fmamk_f32 v175, v165, 0x39800000, v185
	v_rsq_f32_e32 v175, v175
	s_nop 0
	v_mul_f32_e32 v175, 0x41e1c71c, v175
	v_lshlrev_b32_e32 v167, 16, v188
	v_and_b32_e32 v168, 0xffff0000, v188
	v_lshlrev_b32_e32 v169, 16, v189
	v_and_b32_e32 v170, 0xffff0000, v189
	v_add_f32_e32 v126, v126, v167
	v_add_f32_e32 v127, v127, v168
	v_add_f32_e32 v128, v128, v169
	v_add_f32_e32 v129, v129, v170
	v_cvt_pk_bf16_f32 v204, v126, v127
	v_cvt_pk_bf16_f32 v205, v128, v129
	v_mul_f32_e32 v171, v175, v126
	v_mul_f32_e32 v172, v175, v127
	v_mul_f32_e32 v173, v175, v128
	v_mul_f32_e32 v174, v175, v129
	v_rndne_f32_e32 v171, v171
	v_rndne_f32_e32 v172, v172
	v_rndne_f32_e32 v173, v173
	v_rndne_f32_e32 v174, v174
	v_med3_f32 v171, v171, s50, v186
	v_med3_f32 v172, v172, s50, v186
	v_med3_f32 v173, v173, s50, v186
	v_med3_f32 v174, v174, s50, v186
	v_cvt_i32_f32_e32 v171, v171
	v_cvt_i32_f32_e32 v172, v172
	v_cvt_i32_f32_e32 v173, v173
	v_cvt_i32_f32_e32 v174, v174
	v_and_b32_e32 v171, 0xff, v171
	v_and_b32_e32 v172, 0xff, v172
	v_and_b32_e32 v173, 0xff, v173
	v_lshl_or_b32 v171, v172, 8, v171
	v_lshl_or_b32 v171, v173, 16, v171
	v_lshl_or_b32 v208, v174, 24, v171
	v_lshlrev_b32_e32 v167, 16, v190
	v_and_b32_e32 v168, 0xffff0000, v190
	v_lshlrev_b32_e32 v169, 16, v191
	v_and_b32_e32 v170, 0xffff0000, v191
	v_add_f32_e32 v122, v122, v167
	v_add_f32_e32 v123, v123, v168
	v_add_f32_e32 v124, v124, v169
	v_add_f32_e32 v125, v125, v170
	v_cvt_pk_bf16_f32 v206, v122, v123
	v_cvt_pk_bf16_f32 v207, v124, v125
	v_mul_f32_e32 v171, v175, v122
	v_mul_f32_e32 v172, v175, v123
	v_mul_f32_e32 v173, v175, v124
	v_mul_f32_e32 v174, v175, v125
	v_rndne_f32_e32 v171, v171
	v_rndne_f32_e32 v172, v172
	v_rndne_f32_e32 v173, v173
	v_rndne_f32_e32 v174, v174
	v_med3_f32 v171, v171, s50, v186
	v_med3_f32 v172, v172, s50, v186
	v_med3_f32 v173, v173, s50, v186
	v_med3_f32 v174, v174, s50, v186
	v_cvt_i32_f32_e32 v171, v171
	v_cvt_i32_f32_e32 v172, v172
	v_cvt_i32_f32_e32 v173, v173
	v_cvt_i32_f32_e32 v174, v174
	v_and_b32_e32 v171, 0xff, v171
	v_and_b32_e32 v172, 0xff, v172
	v_and_b32_e32 v173, 0xff, v173
	v_lshl_or_b32 v171, v172, 8, v171
	v_lshl_or_b32 v171, v173, 16, v171
	v_lshl_or_b32 v209, v174, 24, v171
	global_store_dwordx4 v163, v[204:207], s[86:87]
	global_store_dwordx2 v164, v[208:209], s[88:89]
	s_nop 0
	v_lshlrev_b32_e32 v167, 16, v192
	v_and_b32_e32 v168, 0xffff0000, v192
	v_lshlrev_b32_e32 v169, 16, v193
	v_and_b32_e32 v170, 0xffff0000, v193
	v_add_f32_e32 v118, v118, v167
	v_add_f32_e32 v119, v119, v168
	v_add_f32_e32 v120, v120, v169
	v_add_f32_e32 v121, v121, v170
	v_cvt_pk_bf16_f32 v204, v118, v119
	v_cvt_pk_bf16_f32 v205, v120, v121
	v_mul_f32_e32 v171, v175, v118
	v_mul_f32_e32 v172, v175, v119
	v_mul_f32_e32 v173, v175, v120
	v_mul_f32_e32 v174, v175, v121
	v_rndne_f32_e32 v171, v171
	v_rndne_f32_e32 v172, v172
	v_rndne_f32_e32 v173, v173
	v_rndne_f32_e32 v174, v174
	v_med3_f32 v171, v171, s50, v186
	v_med3_f32 v172, v172, s50, v186
	v_med3_f32 v173, v173, s50, v186
	v_med3_f32 v174, v174, s50, v186
	v_cvt_i32_f32_e32 v171, v171
	v_cvt_i32_f32_e32 v172, v172
	v_cvt_i32_f32_e32 v173, v173
	v_cvt_i32_f32_e32 v174, v174
	v_and_b32_e32 v171, 0xff, v171
	v_and_b32_e32 v172, 0xff, v172
	v_and_b32_e32 v173, 0xff, v173
	v_lshl_or_b32 v171, v172, 8, v171
	v_lshl_or_b32 v171, v173, 16, v171
	v_lshl_or_b32 v208, v174, 24, v171
	v_lshlrev_b32_e32 v167, 16, v194
	v_and_b32_e32 v168, 0xffff0000, v194
	v_lshlrev_b32_e32 v169, 16, v195
	v_and_b32_e32 v170, 0xffff0000, v195
	v_add_f32_e32 v114, v114, v167
	v_add_f32_e32 v115, v115, v168
	v_add_f32_e32 v116, v116, v169
	v_add_f32_e32 v117, v117, v170
	v_cvt_pk_bf16_f32 v206, v114, v115
	v_cvt_pk_bf16_f32 v207, v116, v117
	v_mul_f32_e32 v171, v175, v114
	v_mul_f32_e32 v172, v175, v115
	v_mul_f32_e32 v173, v175, v116
	v_mul_f32_e32 v174, v175, v117
	v_rndne_f32_e32 v171, v171
	v_rndne_f32_e32 v172, v172
	v_rndne_f32_e32 v173, v173
	v_rndne_f32_e32 v174, v174
	v_med3_f32 v171, v171, s50, v186
	v_med3_f32 v172, v172, s50, v186
	v_med3_f32 v173, v173, s50, v186
	v_med3_f32 v174, v174, s50, v186
	v_cvt_i32_f32_e32 v171, v171
	v_cvt_i32_f32_e32 v172, v172
	v_cvt_i32_f32_e32 v173, v173
	v_cvt_i32_f32_e32 v174, v174
	v_and_b32_e32 v171, 0xff, v171
	v_and_b32_e32 v172, 0xff, v172
	v_and_b32_e32 v173, 0xff, v173
	v_lshl_or_b32 v171, v172, 8, v171
	v_lshl_or_b32 v171, v173, 16, v171
	v_lshl_or_b32 v209, v174, 24, v171
	global_store_dwordx4 v163, v[204:207], s[86:87] offset:256
	global_store_dwordx2 v164, v[208:209], s[88:89] offset:128
	s_nop 0
	s_add_u32 s86, s86, 0x20000
	s_addc_u32 s87, s87, 0
	s_add_u32 s88, s88, 0x10000
	s_addc_u32 s89, s89, 0
	global_load_dword v165, v162, s[28:29] offset:128
	global_load_dwordx4 v[188:191], v163, s[84:85]
	global_load_dwordx4 v[192:195], v163, s[84:85] offset:256
	s_add_u32 s84, s84, 0x20000
	s_addc_u32 s85, s85, 0
	s_waitcnt vmcnt(7)
; __device__ __forceinline__ u32x4 pack8(const f32x4 a, const f32x4 b) { u32x4 w; w.x = cvt_pk_bf16(a[0], a[1]); w.y = cvt_pk_bf16(a[2], a[3]); w.z = cvt_pk_bf16(b[0], b[1]); w.w = cvt_pk_bf16(b[2], b[3]); return w; }
;     __device__ __forceinline__ void operator()(const f32x4 (&acc)[2][2][4][2], const pg8::Unit& u, int wr, int wc, int fr, int fq) const {
;         const int row0 = u.pm * 256 + wr * 64 + fr, col0 = u.pn * 256 + wc * 32 + 8 * fq;
; #pragma unroll
;         for (int ai = 0; ai < 2; ++ai) {
;             u32x4 hr[4][2]; float q1v[4];
; #pragma unroll
;             for (int m = 0; m < 4; ++m) { q1v[m] = rss1[row0 + ai * 128 + m * 16];
; #pragma unroll
;                 for (int bj = 0; bj < 2; ++bj) hr[m][bj] = *(const u32x4*)(HB + (size_t)(row0 + ai * 128 + m * 16) * DM + col0 + bj * 128); }
; #pragma unroll
;             for (int m = 0; m < 4; ++m) { const float iq = (127.f / QCLIP) * rsqrtf(q1v[m] * (1.f / DM) + EPS);
; #pragma unroll
;                 for (int bj = 0; bj < 2; ++bj) { float hv[8]; unpack8(hr[m][bj], hv); const size_t off = (size_t)(row0 + ai * 128 + m * 16) * DM + col0 + bj * 128;
;                     f32x4 h0 = acc[ai][bj][m][0], h1 = acc[ai][bj][m][1];
; #pragma unroll
;                     for (int e = 0; e < 4; ++e) { h0[e] += hv[e]; h1[e] += hv[4 + e]; }
;                     *(u32x4*)(HB + off) = pack8(h0, h1);
;                     f32x4 q0, q1;
; #pragma unroll
;                     for (int ee = 0; ee < 4; ++ee) { q0[ee] = fminf(fmaxf(rintf(h0[ee] * iq), -127.f), 127.f); q1[ee] = fminf(fmaxf(rintf(h1[ee] * iq), -127.f), 127.f); }
;                     *(u32x2*)(HQ + off) = pack8_i8(q0, q1); } }
	v_fmamk_f32 v175, v166, 0x39800000, v185
	v_rsq_f32_e32 v175, v175
	s_nop 0
	v_mul_f32_e32 v175, 0x41e1c71c, v175
	v_lshlrev_b32_e32 v167, 16, v196
	v_and_b32_e32 v168, 0xffff0000, v196
	v_lshlrev_b32_e32 v169, 16, v197
	v_and_b32_e32 v170, 0xffff0000, v197
	v_add_f32_e32 v110, v110, v167
	v_add_f32_e32 v111, v111, v168
	v_add_f32_e32 v112, v112, v169
	v_add_f32_e32 v113, v113, v170
	v_cvt_pk_bf16_f32 v204, v110, v111
	v_cvt_pk_bf16_f32 v205, v112, v113
	v_mul_f32_e32 v171, v175, v110
	v_mul_f32_e32 v172, v175, v111
	v_mul_f32_e32 v173, v175, v112
	v_mul_f32_e32 v174, v175, v113
	v_rndne_f32_e32 v171, v171
	v_rndne_f32_e32 v172, v172
	v_rndne_f32_e32 v173, v173
	v_rndne_f32_e32 v174, v174
	v_med3_f32 v171, v171, s50, v186
	v_med3_f32 v172, v172, s50, v186
	v_med3_f32 v173, v173, s50, v186
	v_med3_f32 v174, v174, s50, v186
	v_cvt_i32_f32_e32 v171, v171
	v_cvt_i32_f32_e32 v172, v172
	v_cvt_i32_f32_e32 v173, v173
	v_cvt_i32_f32_e32 v174, v174
	v_and_b32_e32 v171, 0xff, v171
	v_and_b32_e32 v172, 0xff, v172
	v_and_b32_e32 v173, 0xff, v173
	v_lshl_or_b32 v171, v172, 8, v171
	v_lshl_or_b32 v171, v173, 16, v171
	v_lshl_or_b32 v208, v174, 24, v171
	v_lshlrev_b32_e32 v167, 16, v198
	v_and_b32_e32 v168, 0xffff0000, v198
	v_lshlrev_b32_e32 v169, 16, v199
	v_and_b32_e32 v170, 0xffff0000, v199
	v_add_f32_e32 v106, v106, v167
	v_add_f32_e32 v107, v107, v168
	v_add_f32_e32 v108, v108, v169
	v_add_f32_e32 v109, v109, v170
	v_cvt_pk_bf16_f32 v206, v106, v107
	v_cvt_pk_bf16_f32 v207, v108, v109
	v_mul_f32_e32 v171, v175, v106
	v_mul_f32_e32 v172, v175, v107
	v_mul_f32_e32 v173, v175, v108
	v_mul_f32_e32 v174, v175, v109
	v_rndne_f32_e32 v171, v171
	v_rndne_f32_e32 v172, v172
	v_rndne_f32_e32 v173, v173
	v_rndne_f32_e32 v174, v174
	v_med3_f32 v171, v171, s50, v186
	v_med3_f32 v172, v172, s50, v186
	v_med3_f32 v173, v173, s50, v186
	v_med3_f32 v174, v174, s50, v186
	v_cvt_i32_f32_e32 v171, v171
	v_cvt_i32_f32_e32 v172, v172
	v_cvt_i32_f32_e32 v173, v173
	v_cvt_i32_f32_e32 v174, v174
	v_and_b32_e32 v171, 0xff, v171
	v_and_b32_e32 v172, 0xff, v172
	v_and_b32_e32 v173, 0xff, v173
	v_lshl_or_b32 v171, v172, 8, v171
	v_lshl_or_b32 v171, v173, 16, v171
	v_lshl_or_b32 v209, v174, 24, v171
	global_store_dwordx4 v163, v[204:207], s[86:87]
	global_store_dwordx2 v164, v[208:209], s[88:89]
	s_nop 0
	v_lshlrev_b32_e32 v167, 16, v200
	v_and_b32_e32 v168, 0xffff0000, v200
	v_lshlrev_b32_e32 v169, 16, v201
	v_and_b32_e32 v170, 0xffff0000, v201
	v_add_f32_e32 v102, v102, v167
	v_add_f32_e32 v103, v103, v168
	v_add_f32_e32 v104, v104, v169
	v_add_f32_e32 v105, v105, v170
	v_cvt_pk_bf16_f32 v204, v102, v103
	v_cvt_pk_bf16_f32 v205, v104, v105
	v_mul_f32_e32 v171, v175, v102
	v_mul_f32_e32 v172, v175, v103
	v_mul_f32_e32 v173, v175, v104
	v_mul_f32_e32 v174, v175, v105
	v_rndne_f32_e32 v171, v171
	v_rndne_f32_e32 v172, v172
	v_rndne_f32_e32 v173, v173
	v_rndne_f32_e32 v174, v174
	v_med3_f32 v171, v171, s50, v186
	v_med3_f32 v172, v172, s50, v186
	v_med3_f32 v173, v173, s50, v186
	v_med3_f32 v174, v174, s50, v186
	v_cvt_i32_f32_e32 v171, v171
	v_cvt_i32_f32_e32 v172, v172
	v_cvt_i32_f32_e32 v173, v173
	v_cvt_i32_f32_e32 v174, v174
	v_and_b32_e32 v171, 0xff, v171
	v_and_b32_e32 v172, 0xff, v172
	v_and_b32_e32 v173, 0xff, v173
	v_lshl_or_b32 v171, v172, 8, v171
	v_lshl_or_b32 v171, v173, 16, v171
	v_lshl_or_b32 v208, v174, 24, v171
	v_lshlrev_b32_e32 v167, 16, v202
	v_and_b32_e32 v168, 0xffff0000, v202
	v_lshlrev_b32_e32 v169, 16, v203
	v_and_b32_e32 v170, 0xffff0000, v203
	v_add_f32_e32 v98, v98, v167
	v_add_f32_e32 v99, v99, v168
	v_add_f32_e32 v100, v100, v169
	v_add_f32_e32 v101, v101, v170
	v_cvt_pk_bf16_f32 v206, v98, v99
	v_cvt_pk_bf16_f32 v207, v100, v101
	v_mul_f32_e32 v171, v175, v98
	v_mul_f32_e32 v172, v175, v99
	v_mul_f32_e32 v173, v175, v100
	v_mul_f32_e32 v174, v175, v101
	v_rndne_f32_e32 v171, v171
	v_rndne_f32_e32 v172, v172
	v_rndne_f32_e32 v173, v173
	v_rndne_f32_e32 v174, v174
	v_med3_f32 v171, v171, s50, v186
	v_med3_f32 v172, v172, s50, v186
	v_med3_f32 v173, v173, s50, v186
	v_med3_f32 v174, v174, s50, v186
	v_cvt_i32_f32_e32 v171, v171
	v_cvt_i32_f32_e32 v172, v172
	v_cvt_i32_f32_e32 v173, v173
	v_cvt_i32_f32_e32 v174, v174
	v_and_b32_e32 v171, 0xff, v171
	v_and_b32_e32 v172, 0xff, v172
	v_and_b32_e32 v173, 0xff, v173
	v_lshl_or_b32 v171, v172, 8, v171
	v_lshl_or_b32 v171, v173, 16, v171
	v_lshl_or_b32 v209, v174, 24, v171
	global_store_dwordx4 v163, v[204:207], s[86:87] offset:256
	global_store_dwordx2 v164, v[208:209], s[88:89] offset:128
	s_nop 0
	s_add_u32 s86, s86, 0x20000
	s_addc_u32 s87, s87, 0
	s_add_u32 s88, s88, 0x10000
	s_addc_u32 s89, s89, 0
	global_load_dword v166, v162, s[28:29] offset:192
	global_load_dwordx4 v[196:199], v163, s[84:85]
	global_load_dwordx4 v[200:203], v163, s[84:85] offset:256
	s_add_u32 s84, s84, 0xa0000
	s_addc_u32 s85, s85, 0
	s_waitcnt vmcnt(7)
; __device__ __forceinline__ u32x4 pack8(const f32x4 a, const f32x4 b) { u32x4 w; w.x = cvt_pk_bf16(a[0], a[1]); w.y = cvt_pk_bf16(a[2], a[3]); w.z = cvt_pk_bf16(b[0], b[1]); w.w = cvt_pk_bf16(b[2], b[3]); return w; }
;     __device__ __forceinline__ void operator()(const f32x4 (&acc)[2][2][4][2], const pg8::Unit& u, int wr, int wc, int fr, int fq) const {
;         const int row0 = u.pm * 256 + wr * 64 + fr, col0 = u.pn * 256 + wc * 32 + 8 * fq;
; #pragma unroll
;         for (int ai = 0; ai < 2; ++ai) {
;             u32x4 hr[4][2]; float q1v[4];
; #pragma unroll
;             for (int m = 0; m < 4; ++m) { q1v[m] = rss1[row0 + ai * 128 + m * 16];
; #pragma unroll
;                 for (int bj = 0; bj < 2; ++bj) hr[m][bj] = *(const u32x4*)(HB + (size_t)(row0 + ai * 128 + m * 16) * DM + col0 + bj * 128); }
; #pragma unroll
;             for (int m = 0; m < 4; ++m) { const float iq = (127.f / QCLIP) * rsqrtf(q1v[m] * (1.f / DM) + EPS);
; #pragma unroll
;                 for (int bj = 0; bj < 2; ++bj) { float hv[8]; unpack8(hr[m][bj], hv); const size_t off = (size_t)(row0 + ai * 128 + m * 16) * DM + col0 + bj * 128;
;                     f32x4 h0 = acc[ai][bj][m][0], h1 = acc[ai][bj][m][1];
; #pragma unroll
;                     for (int e = 0; e < 4; ++e) { h0[e] += hv[e]; h1[e] += hv[4 + e]; }
;                     *(u32x4*)(HB + off) = pack8(h0, h1);
;                     f32x4 q0, q1;
; #pragma unroll
;                     for (int ee = 0; ee < 4; ++ee) { q0[ee] = fminf(fmaxf(rintf(h0[ee] * iq), -127.f), 127.f); q1[ee] = fminf(fmaxf(rintf(h1[ee] * iq), -127.f), 127.f); }
;                     *(u32x2*)(HQ + off) = pack8_i8(q0, q1); } }
	v_fmamk_f32 v175, v165, 0x39800000, v185
	v_rsq_f32_e32 v175, v175
	s_nop 0
	v_mul_f32_e32 v175, 0x41e1c71c, v175
	v_lshlrev_b32_e32 v167, 16, v188
	v_and_b32_e32 v168, 0xffff0000, v188
	v_lshlrev_b32_e32 v169, 16, v189
	v_and_b32_e32 v170, 0xffff0000, v189
	v_add_f32_e32 v94, v94, v167
	v_add_f32_e32 v95, v95, v168
	v_add_f32_e32 v96, v96, v169
	v_add_f32_e32 v97, v97, v170
	v_cvt_pk_bf16_f32 v204, v94, v95
	v_cvt_pk_bf16_f32 v205, v96, v97
	v_mul_f32_e32 v171, v175, v94
	v_mul_f32_e32 v172, v175, v95
	v_mul_f32_e32 v173, v175, v96
	v_mul_f32_e32 v174, v175, v97
	v_rndne_f32_e32 v171, v171
	v_rndne_f32_e32 v172, v172
	v_rndne_f32_e32 v173, v173
	v_rndne_f32_e32 v174, v174
	v_med3_f32 v171, v171, s50, v186
	v_med3_f32 v172, v172, s50, v186
	v_med3_f32 v173, v173, s50, v186
	v_med3_f32 v174, v174, s50, v186
	v_cvt_i32_f32_e32 v171, v171
	v_cvt_i32_f32_e32 v172, v172
	v_cvt_i32_f32_e32 v173, v173
	v_cvt_i32_f32_e32 v174, v174
	v_and_b32_e32 v171, 0xff, v171
	v_and_b32_e32 v172, 0xff, v172
	v_and_b32_e32 v173, 0xff, v173
	v_lshl_or_b32 v171, v172, 8, v171
	v_lshl_or_b32 v171, v173, 16, v171
	v_lshl_or_b32 v208, v174, 24, v171
	v_lshlrev_b32_e32 v167, 16, v190
	v_and_b32_e32 v168, 0xffff0000, v190
	v_lshlrev_b32_e32 v169, 16, v191
	v_and_b32_e32 v170, 0xffff0000, v191
	v_add_f32_e32 v90, v90, v167
	v_add_f32_e32 v91, v91, v168
	v_add_f32_e32 v92, v92, v169
	v_add_f32_e32 v93, v93, v170
	v_cvt_pk_bf16_f32 v206, v90, v91
	v_cvt_pk_bf16_f32 v207, v92, v93
	v_mul_f32_e32 v171, v175, v90
	v_mul_f32_e32 v172, v175, v91
	v_mul_f32_e32 v173, v175, v92
	v_mul_f32_e32 v174, v175, v93
	v_rndne_f32_e32 v171, v171
	v_rndne_f32_e32 v172, v172
	v_rndne_f32_e32 v173, v173
	v_rndne_f32_e32 v174, v174
	v_med3_f32 v171, v171, s50, v186
	v_med3_f32 v172, v172, s50, v186
	v_med3_f32 v173, v173, s50, v186
	v_med3_f32 v174, v174, s50, v186
	v_cvt_i32_f32_e32 v171, v171
	v_cvt_i32_f32_e32 v172, v172
	v_cvt_i32_f32_e32 v173, v173
	v_cvt_i32_f32_e32 v174, v174
	v_and_b32_e32 v171, 0xff, v171
	v_and_b32_e32 v172, 0xff, v172
	v_and_b32_e32 v173, 0xff, v173
	v_lshl_or_b32 v171, v172, 8, v171
	v_lshl_or_b32 v171, v173, 16, v171
	v_lshl_or_b32 v209, v174, 24, v171
	global_store_dwordx4 v163, v[204:207], s[86:87]
	global_store_dwordx2 v164, v[208:209], s[88:89]
	s_nop 0
	v_lshlrev_b32_e32 v167, 16, v192
	v_and_b32_e32 v168, 0xffff0000, v192
	v_lshlrev_b32_e32 v169, 16, v193
	v_and_b32_e32 v170, 0xffff0000, v193
	v_add_f32_e32 v86, v86, v167
	v_add_f32_e32 v87, v87, v168
	v_add_f32_e32 v88, v88, v169
	v_add_f32_e32 v89, v89, v170
	v_cvt_pk_bf16_f32 v204, v86, v87
	v_cvt_pk_bf16_f32 v205, v88, v89
	v_mul_f32_e32 v171, v175, v86
	v_mul_f32_e32 v172, v175, v87
	v_mul_f32_e32 v173, v175, v88
	v_mul_f32_e32 v174, v175, v89
	v_rndne_f32_e32 v171, v171
	v_rndne_f32_e32 v172, v172
	v_rndne_f32_e32 v173, v173
	v_rndne_f32_e32 v174, v174
	v_med3_f32 v171, v171, s50, v186
	v_med3_f32 v172, v172, s50, v186
	v_med3_f32 v173, v173, s50, v186
	v_med3_f32 v174, v174, s50, v186
	v_cvt_i32_f32_e32 v171, v171
	v_cvt_i32_f32_e32 v172, v172
	v_cvt_i32_f32_e32 v173, v173
	v_cvt_i32_f32_e32 v174, v174
	v_and_b32_e32 v171, 0xff, v171
	v_and_b32_e32 v172, 0xff, v172
	v_and_b32_e32 v173, 0xff, v173
	v_lshl_or_b32 v171, v172, 8, v171
	v_lshl_or_b32 v171, v173, 16, v171
	v_lshl_or_b32 v208, v174, 24, v171
	v_lshlrev_b32_e32 v167, 16, v194
	v_and_b32_e32 v168, 0xffff0000, v194
	v_lshlrev_b32_e32 v169, 16, v195
	v_and_b32_e32 v170, 0xffff0000, v195
	v_add_f32_e32 v82, v82, v167
	v_add_f32_e32 v83, v83, v168
	v_add_f32_e32 v84, v84, v169
	v_add_f32_e32 v85, v85, v170
	v_cvt_pk_bf16_f32 v206, v82, v83
	v_cvt_pk_bf16_f32 v207, v84, v85
	v_mul_f32_e32 v171, v175, v82
	v_mul_f32_e32 v172, v175, v83
	v_mul_f32_e32 v173, v175, v84
	v_mul_f32_e32 v174, v175, v85
	v_rndne_f32_e32 v171, v171
	v_rndne_f32_e32 v172, v172
	v_rndne_f32_e32 v173, v173
	v_rndne_f32_e32 v174, v174
	v_med3_f32 v171, v171, s50, v186
	v_med3_f32 v172, v172, s50, v186
	v_med3_f32 v173, v173, s50, v186
	v_med3_f32 v174, v174, s50, v186
	v_cvt_i32_f32_e32 v171, v171
	v_cvt_i32_f32_e32 v172, v172
	v_cvt_i32_f32_e32 v173, v173
	v_cvt_i32_f32_e32 v174, v174
	v_and_b32_e32 v171, 0xff, v171
	v_and_b32_e32 v172, 0xff, v172
	v_and_b32_e32 v173, 0xff, v173
	v_lshl_or_b32 v171, v172, 8, v171
	v_lshl_or_b32 v171, v173, 16, v171
	v_lshl_or_b32 v209, v174, 24, v171
	global_store_dwordx4 v163, v[204:207], s[86:87] offset:256
	global_store_dwordx2 v164, v[208:209], s[88:89] offset:128
	s_nop 0
	s_add_u32 s86, s86, 0x20000
	s_addc_u32 s87, s87, 0
	s_add_u32 s88, s88, 0x10000
	s_addc_u32 s89, s89, 0
	global_load_dword v165, v162, s[28:29] offset:512
	global_load_dwordx4 v[188:191], v163, s[84:85]
	global_load_dwordx4 v[192:195], v163, s[84:85] offset:256
	s_add_u32 s84, s84, 0x20000
	s_addc_u32 s85, s85, 0
	s_waitcnt vmcnt(7)
; __device__ __forceinline__ u32x4 pack8(const f32x4 a, const f32x4 b) { u32x4 w; w.x = cvt_pk_bf16(a[0], a[1]); w.y = cvt_pk_bf16(a[2], a[3]); w.z = cvt_pk_bf16(b[0], b[1]); w.w = cvt_pk_bf16(b[2], b[3]); return w; }
;     __device__ __forceinline__ void operator()(const f32x4 (&acc)[2][2][4][2], const pg8::Unit& u, int wr, int wc, int fr, int fq) const {
;         const int row0 = u.pm * 256 + wr * 64 + fr, col0 = u.pn * 256 + wc * 32 + 8 * fq;
; #pragma unroll
;         for (int ai = 0; ai < 2; ++ai) {
;             u32x4 hr[4][2]; float q1v[4];
; #pragma unroll
;             for (int m = 0; m < 4; ++m) { q1v[m] = rss1[row0 + ai * 128 + m * 16];
; #pragma unroll
;                 for (int bj = 0; bj < 2; ++bj) hr[m][bj] = *(const u32x4*)(HB + (size_t)(row0 + ai * 128 + m * 16) * DM + col0 + bj * 128); }
; #pragma unroll
;             for (int m = 0; m < 4; ++m) { const float iq = (127.f / QCLIP) * rsqrtf(q1v[m] * (1.f / DM) + EPS);
; #pragma unroll
;                 for (int bj = 0; bj < 2; ++bj) { float hv[8]; unpack8(hr[m][bj], hv); const size_t off = (size_t)(row0 + ai * 128 + m * 16) * DM + col0 + bj * 128;
;                     f32x4 h0 = acc[ai][bj][m][0], h1 = acc[ai][bj][m][1];
; #pragma unroll
;                     for (int e = 0; e < 4; ++e) { h0[e] += hv[e]; h1[e] += hv[4 + e]; }
;                     *(u32x4*)(HB + off) = pack8(h0, h1);
;                     f32x4 q0, q1;
; #pragma unroll
;                     for (int ee = 0; ee < 4; ++ee) { q0[ee] = fminf(fmaxf(rintf(h0[ee] * iq), -127.f), 127.f); q1[ee] = fminf(fmaxf(rintf(h1[ee] * iq), -127.f), 127.f); }
;                     *(u32x2*)(HQ + off) = pack8_i8(q0, q1); } }
	v_fmamk_f32 v175, v166, 0x39800000, v185
	v_rsq_f32_e32 v175, v175
	s_nop 0
	v_mul_f32_e32 v175, 0x41e1c71c, v175
	v_lshlrev_b32_e32 v167, 16, v196
	v_and_b32_e32 v168, 0xffff0000, v196
	v_lshlrev_b32_e32 v169, 16, v197
	v_and_b32_e32 v170, 0xffff0000, v197
	v_add_f32_e32 v78, v78, v167
	v_add_f32_e32 v79, v79, v168
	v_add_f32_e32 v80, v80, v169
	v_add_f32_e32 v81, v81, v170
	v_cvt_pk_bf16_f32 v204, v78, v79
	v_cvt_pk_bf16_f32 v205, v80, v81
	v_mul_f32_e32 v171, v175, v78
	v_mul_f32_e32 v172, v175, v79
	v_mul_f32_e32 v173, v175, v80
	v_mul_f32_e32 v174, v175, v81
	v_rndne_f32_e32 v171, v171
	v_rndne_f32_e32 v172, v172
	v_rndne_f32_e32 v173, v173
	v_rndne_f32_e32 v174, v174
	v_med3_f32 v171, v171, s50, v186
	v_med3_f32 v172, v172, s50, v186
	v_med3_f32 v173, v173, s50, v186
	v_med3_f32 v174, v174, s50, v186
	v_cvt_i32_f32_e32 v171, v171
	v_cvt_i32_f32_e32 v172, v172
	v_cvt_i32_f32_e32 v173, v173
	v_cvt_i32_f32_e32 v174, v174
	v_and_b32_e32 v171, 0xff, v171
	v_and_b32_e32 v172, 0xff, v172
	v_and_b32_e32 v173, 0xff, v173
	v_lshl_or_b32 v171, v172, 8, v171
	v_lshl_or_b32 v171, v173, 16, v171
	v_lshl_or_b32 v208, v174, 24, v171
	v_lshlrev_b32_e32 v167, 16, v198
	v_and_b32_e32 v168, 0xffff0000, v198
	v_lshlrev_b32_e32 v169, 16, v199
	v_and_b32_e32 v170, 0xffff0000, v199
	v_add_f32_e32 v74, v74, v167
	v_add_f32_e32 v75, v75, v168
	v_add_f32_e32 v76, v76, v169
	v_add_f32_e32 v77, v77, v170
	v_cvt_pk_bf16_f32 v206, v74, v75
	v_cvt_pk_bf16_f32 v207, v76, v77
	v_mul_f32_e32 v171, v175, v74
	v_mul_f32_e32 v172, v175, v75
	v_mul_f32_e32 v173, v175, v76
	v_mul_f32_e32 v174, v175, v77
	v_rndne_f32_e32 v171, v171
	v_rndne_f32_e32 v172, v172
	v_rndne_f32_e32 v173, v173
	v_rndne_f32_e32 v174, v174
	v_med3_f32 v171, v171, s50, v186
	v_med3_f32 v172, v172, s50, v186
	v_med3_f32 v173, v173, s50, v186
	v_med3_f32 v174, v174, s50, v186
	v_cvt_i32_f32_e32 v171, v171
	v_cvt_i32_f32_e32 v172, v172
	v_cvt_i32_f32_e32 v173, v173
	v_cvt_i32_f32_e32 v174, v174
	v_and_b32_e32 v171, 0xff, v171
	v_and_b32_e32 v172, 0xff, v172
	v_and_b32_e32 v173, 0xff, v173
	v_lshl_or_b32 v171, v172, 8, v171
	v_lshl_or_b32 v171, v173, 16, v171
	v_lshl_or_b32 v209, v174, 24, v171
	global_store_dwordx4 v163, v[204:207], s[86:87]
	global_store_dwordx2 v164, v[208:209], s[88:89]
	s_nop 0
	v_lshlrev_b32_e32 v167, 16, v200
	v_and_b32_e32 v168, 0xffff0000, v200
	v_lshlrev_b32_e32 v169, 16, v201
	v_and_b32_e32 v170, 0xffff0000, v201
	v_add_f32_e32 v70, v70, v167
	v_add_f32_e32 v71, v71, v168
	v_add_f32_e32 v72, v72, v169
	v_add_f32_e32 v73, v73, v170
	v_cvt_pk_bf16_f32 v204, v70, v71
	v_cvt_pk_bf16_f32 v205, v72, v73
	v_mul_f32_e32 v171, v175, v70
	v_mul_f32_e32 v172, v175, v71
	v_mul_f32_e32 v173, v175, v72
	v_mul_f32_e32 v174, v175, v73
	v_rndne_f32_e32 v171, v171
	v_rndne_f32_e32 v172, v172
	v_rndne_f32_e32 v173, v173
	v_rndne_f32_e32 v174, v174
	v_med3_f32 v171, v171, s50, v186
	v_med3_f32 v172, v172, s50, v186
	v_med3_f32 v173, v173, s50, v186
	v_med3_f32 v174, v174, s50, v186
	v_cvt_i32_f32_e32 v171, v171
	v_cvt_i32_f32_e32 v172, v172
	v_cvt_i32_f32_e32 v173, v173
	v_cvt_i32_f32_e32 v174, v174
	v_and_b32_e32 v171, 0xff, v171
	v_and_b32_e32 v172, 0xff, v172
	v_and_b32_e32 v173, 0xff, v173
	v_lshl_or_b32 v171, v172, 8, v171
	v_lshl_or_b32 v171, v173, 16, v171
	v_lshl_or_b32 v208, v174, 24, v171
	v_lshlrev_b32_e32 v167, 16, v202
	v_and_b32_e32 v168, 0xffff0000, v202
	v_lshlrev_b32_e32 v169, 16, v203
	v_and_b32_e32 v170, 0xffff0000, v203
	v_add_f32_e32 v66, v66, v167
	v_add_f32_e32 v67, v67, v168
	v_add_f32_e32 v68, v68, v169
	v_add_f32_e32 v69, v69, v170
	v_cvt_pk_bf16_f32 v206, v66, v67
	v_cvt_pk_bf16_f32 v207, v68, v69
	v_mul_f32_e32 v171, v175, v66
	v_mul_f32_e32 v172, v175, v67
	v_mul_f32_e32 v173, v175, v68
	v_mul_f32_e32 v174, v175, v69
	v_rndne_f32_e32 v171, v171
	v_rndne_f32_e32 v172, v172
	v_rndne_f32_e32 v173, v173
	v_rndne_f32_e32 v174, v174
	v_med3_f32 v171, v171, s50, v186
	v_med3_f32 v172, v172, s50, v186
	v_med3_f32 v173, v173, s50, v186
	v_med3_f32 v174, v174, s50, v186
	v_cvt_i32_f32_e32 v171, v171
	v_cvt_i32_f32_e32 v172, v172
	v_cvt_i32_f32_e32 v173, v173
	v_cvt_i32_f32_e32 v174, v174
	v_and_b32_e32 v171, 0xff, v171
	v_and_b32_e32 v172, 0xff, v172
	v_and_b32_e32 v173, 0xff, v173
	v_lshl_or_b32 v171, v172, 8, v171
	v_lshl_or_b32 v171, v173, 16, v171
	v_lshl_or_b32 v209, v174, 24, v171
	global_store_dwordx4 v163, v[204:207], s[86:87] offset:256
	global_store_dwordx2 v164, v[208:209], s[88:89] offset:128
	s_nop 0
	s_add_u32 s86, s86, 0xa0000
	s_addc_u32 s87, s87, 0
	s_add_u32 s88, s88, 0x50000
	s_addc_u32 s89, s89, 0
	global_load_dword v166, v162, s[28:29] offset:576
	global_load_dwordx4 v[196:199], v163, s[84:85]
	global_load_dwordx4 v[200:203], v163, s[84:85] offset:256
	s_add_u32 s84, s84, 0x20000
	s_addc_u32 s85, s85, 0
	s_waitcnt vmcnt(7)
; __device__ __forceinline__ u32x4 pack8(const f32x4 a, const f32x4 b) { u32x4 w; w.x = cvt_pk_bf16(a[0], a[1]); w.y = cvt_pk_bf16(a[2], a[3]); w.z = cvt_pk_bf16(b[0], b[1]); w.w = cvt_pk_bf16(b[2], b[3]); return w; }
;     __device__ __forceinline__ void operator()(const f32x4 (&acc)[2][2][4][2], const pg8::Unit& u, int wr, int wc, int fr, int fq) const {
;         const int row0 = u.pm * 256 + wr * 64 + fr, col0 = u.pn * 256 + wc * 32 + 8 * fq;
; #pragma unroll
;         for (int ai = 0; ai < 2; ++ai) {
;             u32x4 hr[4][2]; float q1v[4];
; #pragma unroll
;             for (int m = 0; m < 4; ++m) { q1v[m] = rss1[row0 + ai * 128 + m * 16];
; #pragma unroll
;                 for (int bj = 0; bj < 2; ++bj) hr[m][bj] = *(const u32x4*)(HB + (size_t)(row0 + ai * 128 + m * 16) * DM + col0 + bj * 128); }
; #pragma unroll
;             for (int m = 0; m < 4; ++m) { const float iq = (127.f / QCLIP) * rsqrtf(q1v[m] * (1.f / DM) + EPS);
; #pragma unroll
;                 for (int bj = 0; bj < 2; ++bj) { float hv[8]; unpack8(hr[m][bj], hv); const size_t off = (size_t)(row0 + ai * 128 + m * 16) * DM + col0 + bj * 128;
;                     f32x4 h0 = acc[ai][bj][m][0], h1 = acc[ai][bj][m][1];
; #pragma unroll
;                     for (int e = 0; e < 4; ++e) { h0[e] += hv[e]; h1[e] += hv[4 + e]; }
;                     *(u32x4*)(HB + off) = pack8(h0, h1);
;                     f32x4 q0, q1;
; #pragma unroll
;                     for (int ee = 0; ee < 4; ++ee) { q0[ee] = fminf(fmaxf(rintf(h0[ee] * iq), -127.f), 127.f); q1[ee] = fminf(fmaxf(rintf(h1[ee] * iq), -127.f), 127.f); }
;                     *(u32x2*)(HQ + off) = pack8_i8(q0, q1); } }
	v_fmamk_f32 v175, v165, 0x39800000, v185
	v_rsq_f32_e32 v175, v175
	s_nop 0
	v_mul_f32_e32 v175, 0x41e1c71c, v175
	v_lshlrev_b32_e32 v167, 16, v188
	v_and_b32_e32 v168, 0xffff0000, v188
	v_lshlrev_b32_e32 v169, 16, v189
	v_and_b32_e32 v170, 0xffff0000, v189
	v_add_f32_e32 v62, v62, v167
	v_add_f32_e32 v63, v63, v168
	v_add_f32_e32 v64, v64, v169
	v_add_f32_e32 v65, v65, v170
	v_cvt_pk_bf16_f32 v204, v62, v63
	v_cvt_pk_bf16_f32 v205, v64, v65
	v_mul_f32_e32 v171, v175, v62
	v_mul_f32_e32 v172, v175, v63
	v_mul_f32_e32 v173, v175, v64
	v_mul_f32_e32 v174, v175, v65
	v_rndne_f32_e32 v171, v171
	v_rndne_f32_e32 v172, v172
	v_rndne_f32_e32 v173, v173
	v_rndne_f32_e32 v174, v174
	v_med3_f32 v171, v171, s50, v186
	v_med3_f32 v172, v172, s50, v186
	v_med3_f32 v173, v173, s50, v186
	v_med3_f32 v174, v174, s50, v186
	v_cvt_i32_f32_e32 v171, v171
	v_cvt_i32_f32_e32 v172, v172
	v_cvt_i32_f32_e32 v173, v173
	v_cvt_i32_f32_e32 v174, v174
	v_and_b32_e32 v171, 0xff, v171
	v_and_b32_e32 v172, 0xff, v172
	v_and_b32_e32 v173, 0xff, v173
	v_lshl_or_b32 v171, v172, 8, v171
	v_lshl_or_b32 v171, v173, 16, v171
	v_lshl_or_b32 v208, v174, 24, v171
	v_lshlrev_b32_e32 v167, 16, v190
	v_and_b32_e32 v168, 0xffff0000, v190
	v_lshlrev_b32_e32 v169, 16, v191
	v_and_b32_e32 v170, 0xffff0000, v191
	v_add_f32_e32 v58, v58, v167
	v_add_f32_e32 v59, v59, v168
	v_add_f32_e32 v60, v60, v169
	v_add_f32_e32 v61, v61, v170
	v_cvt_pk_bf16_f32 v206, v58, v59
	v_cvt_pk_bf16_f32 v207, v60, v61
	v_mul_f32_e32 v171, v175, v58
	v_mul_f32_e32 v172, v175, v59
	v_mul_f32_e32 v173, v175, v60
	v_mul_f32_e32 v174, v175, v61
	v_rndne_f32_e32 v171, v171
	v_rndne_f32_e32 v172, v172
	v_rndne_f32_e32 v173, v173
	v_rndne_f32_e32 v174, v174
	v_med3_f32 v171, v171, s50, v186
	v_med3_f32 v172, v172, s50, v186
	v_med3_f32 v173, v173, s50, v186
	v_med3_f32 v174, v174, s50, v186
	v_cvt_i32_f32_e32 v171, v171
	v_cvt_i32_f32_e32 v172, v172
	v_cvt_i32_f32_e32 v173, v173
	v_cvt_i32_f32_e32 v174, v174
	v_and_b32_e32 v171, 0xff, v171
	v_and_b32_e32 v172, 0xff, v172
	v_and_b32_e32 v173, 0xff, v173
	v_lshl_or_b32 v171, v172, 8, v171
	v_lshl_or_b32 v171, v173, 16, v171
	v_lshl_or_b32 v209, v174, 24, v171
	global_store_dwordx4 v163, v[204:207], s[86:87]
	global_store_dwordx2 v164, v[208:209], s[88:89]
	s_nop 0
	v_lshlrev_b32_e32 v167, 16, v192
	v_and_b32_e32 v168, 0xffff0000, v192
	v_lshlrev_b32_e32 v169, 16, v193
	v_and_b32_e32 v170, 0xffff0000, v193
	v_add_f32_e32 v54, v54, v167
	v_add_f32_e32 v55, v55, v168
	v_add_f32_e32 v56, v56, v169
	v_add_f32_e32 v57, v57, v170
	v_cvt_pk_bf16_f32 v204, v54, v55
	v_cvt_pk_bf16_f32 v205, v56, v57
	v_mul_f32_e32 v171, v175, v54
	v_mul_f32_e32 v172, v175, v55
	v_mul_f32_e32 v173, v175, v56
	v_mul_f32_e32 v174, v175, v57
	v_rndne_f32_e32 v171, v171
	v_rndne_f32_e32 v172, v172
	v_rndne_f32_e32 v173, v173
	v_rndne_f32_e32 v174, v174
	v_med3_f32 v171, v171, s50, v186
	v_med3_f32 v172, v172, s50, v186
	v_med3_f32 v173, v173, s50, v186
	v_med3_f32 v174, v174, s50, v186
	v_cvt_i32_f32_e32 v171, v171
	v_cvt_i32_f32_e32 v172, v172
	v_cvt_i32_f32_e32 v173, v173
	v_cvt_i32_f32_e32 v174, v174
	v_and_b32_e32 v171, 0xff, v171
	v_and_b32_e32 v172, 0xff, v172
	v_and_b32_e32 v173, 0xff, v173
	v_lshl_or_b32 v171, v172, 8, v171
	v_lshl_or_b32 v171, v173, 16, v171
	v_lshl_or_b32 v208, v174, 24, v171
	v_lshlrev_b32_e32 v167, 16, v194
	v_and_b32_e32 v168, 0xffff0000, v194
	v_lshlrev_b32_e32 v169, 16, v195
	v_and_b32_e32 v170, 0xffff0000, v195
	v_add_f32_e32 v50, v50, v167
	v_add_f32_e32 v51, v51, v168
	v_add_f32_e32 v52, v52, v169
	v_add_f32_e32 v53, v53, v170
	v_cvt_pk_bf16_f32 v206, v50, v51
	v_cvt_pk_bf16_f32 v207, v52, v53
	v_mul_f32_e32 v171, v175, v50
	v_mul_f32_e32 v172, v175, v51
	v_mul_f32_e32 v173, v175, v52
	v_mul_f32_e32 v174, v175, v53
	v_rndne_f32_e32 v171, v171
	v_rndne_f32_e32 v172, v172
	v_rndne_f32_e32 v173, v173
	v_rndne_f32_e32 v174, v174
	v_med3_f32 v171, v171, s50, v186
	v_med3_f32 v172, v172, s50, v186
	v_med3_f32 v173, v173, s50, v186
	v_med3_f32 v174, v174, s50, v186
	v_cvt_i32_f32_e32 v171, v171
	v_cvt_i32_f32_e32 v172, v172
	v_cvt_i32_f32_e32 v173, v173
	v_cvt_i32_f32_e32 v174, v174
	v_and_b32_e32 v171, 0xff, v171
	v_and_b32_e32 v172, 0xff, v172
	v_and_b32_e32 v173, 0xff, v173
	v_lshl_or_b32 v171, v172, 8, v171
	v_lshl_or_b32 v171, v173, 16, v171
	v_lshl_or_b32 v209, v174, 24, v171
	global_store_dwordx4 v163, v[204:207], s[86:87] offset:256
	global_store_dwordx2 v164, v[208:209], s[88:89] offset:128
	s_nop 0
	s_add_u32 s86, s86, 0x20000
	s_addc_u32 s87, s87, 0
	s_add_u32 s88, s88, 0x10000
	s_addc_u32 s89, s89, 0
	global_load_dword v165, v162, s[28:29] offset:640
	global_load_dwordx4 v[188:191], v163, s[84:85]
	global_load_dwordx4 v[192:195], v163, s[84:85] offset:256
	s_add_u32 s84, s84, 0x20000
	s_addc_u32 s85, s85, 0
	s_waitcnt vmcnt(7)
; __device__ __forceinline__ u32x4 pack8(const f32x4 a, const f32x4 b) { u32x4 w; w.x = cvt_pk_bf16(a[0], a[1]); w.y = cvt_pk_bf16(a[2], a[3]); w.z = cvt_pk_bf16(b[0], b[1]); w.w = cvt_pk_bf16(b[2], b[3]); return w; }
;     __device__ __forceinline__ void operator()(const f32x4 (&acc)[2][2][4][2], const pg8::Unit& u, int wr, int wc, int fr, int fq) const {
;         const int row0 = u.pm * 256 + wr * 64 + fr, col0 = u.pn * 256 + wc * 32 + 8 * fq;
; #pragma unroll
;         for (int ai = 0; ai < 2; ++ai) {
;             u32x4 hr[4][2]; float q1v[4];
; #pragma unroll
;             for (int m = 0; m < 4; ++m) { q1v[m] = rss1[row0 + ai * 128 + m * 16];
; #pragma unroll
;                 for (int bj = 0; bj < 2; ++bj) hr[m][bj] = *(const u32x4*)(HB + (size_t)(row0 + ai * 128 + m * 16) * DM + col0 + bj * 128); }
; #pragma unroll
;             for (int m = 0; m < 4; ++m) { const float iq = (127.f / QCLIP) * rsqrtf(q1v[m] * (1.f / DM) + EPS);
; #pragma unroll
;                 for (int bj = 0; bj < 2; ++bj) { float hv[8]; unpack8(hr[m][bj], hv); const size_t off = (size_t)(row0 + ai * 128 + m * 16) * DM + col0 + bj * 128;
;                     f32x4 h0 = acc[ai][bj][m][0], h1 = acc[ai][bj][m][1];
; #pragma unroll
;                     for (int e = 0; e < 4; ++e) { h0[e] += hv[e]; h1[e] += hv[4 + e]; }
;                     *(u32x4*)(HB + off) = pack8(h0, h1);
;                     f32x4 q0, q1;
; #pragma unroll
;                     for (int ee = 0; ee < 4; ++ee) { q0[ee] = fminf(fmaxf(rintf(h0[ee] * iq), -127.f), 127.f); q1[ee] = fminf(fmaxf(rintf(h1[ee] * iq), -127.f), 127.f); }
;                     *(u32x2*)(HQ + off) = pack8_i8(q0, q1); } }
	v_fmamk_f32 v175, v166, 0x39800000, v185
	v_rsq_f32_e32 v175, v175
	s_nop 0
	v_mul_f32_e32 v175, 0x41e1c71c, v175
	v_lshlrev_b32_e32 v167, 16, v196
	v_and_b32_e32 v168, 0xffff0000, v196
	v_lshlrev_b32_e32 v169, 16, v197
	v_and_b32_e32 v170, 0xffff0000, v197
	v_add_f32_e32 v46, v46, v167
	v_add_f32_e32 v47, v47, v168
	v_add_f32_e32 v48, v48, v169
	v_add_f32_e32 v49, v49, v170
	v_cvt_pk_bf16_f32 v204, v46, v47
	v_cvt_pk_bf16_f32 v205, v48, v49
	v_mul_f32_e32 v171, v175, v46
	v_mul_f32_e32 v172, v175, v47
	v_mul_f32_e32 v173, v175, v48
	v_mul_f32_e32 v174, v175, v49
	v_rndne_f32_e32 v171, v171
	v_rndne_f32_e32 v172, v172
	v_rndne_f32_e32 v173, v173
	v_rndne_f32_e32 v174, v174
	v_med3_f32 v171, v171, s50, v186
	v_med3_f32 v172, v172, s50, v186
	v_med3_f32 v173, v173, s50, v186
	v_med3_f32 v174, v174, s50, v186
	v_cvt_i32_f32_e32 v171, v171
	v_cvt_i32_f32_e32 v172, v172
	v_cvt_i32_f32_e32 v173, v173
	v_cvt_i32_f32_e32 v174, v174
	v_and_b32_e32 v171, 0xff, v171
	v_and_b32_e32 v172, 0xff, v172
	v_and_b32_e32 v173, 0xff, v173
	v_lshl_or_b32 v171, v172, 8, v171
	v_lshl_or_b32 v171, v173, 16, v171
	v_lshl_or_b32 v208, v174, 24, v171
	v_lshlrev_b32_e32 v167, 16, v198
	v_and_b32_e32 v168, 0xffff0000, v198
	v_lshlrev_b32_e32 v169, 16, v199
	v_and_b32_e32 v170, 0xffff0000, v199
	v_add_f32_e32 v42, v42, v167
	v_add_f32_e32 v43, v43, v168
	v_add_f32_e32 v44, v44, v169
	v_add_f32_e32 v45, v45, v170
	v_cvt_pk_bf16_f32 v206, v42, v43
	v_cvt_pk_bf16_f32 v207, v44, v45
	v_mul_f32_e32 v171, v175, v42
	v_mul_f32_e32 v172, v175, v43
	v_mul_f32_e32 v173, v175, v44
	v_mul_f32_e32 v174, v175, v45
	v_rndne_f32_e32 v171, v171
	v_rndne_f32_e32 v172, v172
	v_rndne_f32_e32 v173, v173
	v_rndne_f32_e32 v174, v174
	v_med3_f32 v171, v171, s50, v186
	v_med3_f32 v172, v172, s50, v186
	v_med3_f32 v173, v173, s50, v186
	v_med3_f32 v174, v174, s50, v186
	v_cvt_i32_f32_e32 v171, v171
	v_cvt_i32_f32_e32 v172, v172
	v_cvt_i32_f32_e32 v173, v173
	v_cvt_i32_f32_e32 v174, v174
	v_and_b32_e32 v171, 0xff, v171
	v_and_b32_e32 v172, 0xff, v172
	v_and_b32_e32 v173, 0xff, v173
	v_lshl_or_b32 v171, v172, 8, v171
	v_lshl_or_b32 v171, v173, 16, v171
	v_lshl_or_b32 v209, v174, 24, v171
	global_store_dwordx4 v163, v[204:207], s[86:87]
	global_store_dwordx2 v164, v[208:209], s[88:89]
	s_nop 0
	v_lshlrev_b32_e32 v167, 16, v200
	v_and_b32_e32 v168, 0xffff0000, v200
	v_lshlrev_b32_e32 v169, 16, v201
	v_and_b32_e32 v170, 0xffff0000, v201
	v_add_f32_e32 v38, v38, v167
	v_add_f32_e32 v39, v39, v168
	v_add_f32_e32 v40, v40, v169
	v_add_f32_e32 v41, v41, v170
	v_cvt_pk_bf16_f32 v204, v38, v39
	v_cvt_pk_bf16_f32 v205, v40, v41
	v_mul_f32_e32 v171, v175, v38
	v_mul_f32_e32 v172, v175, v39
	v_mul_f32_e32 v173, v175, v40
	v_mul_f32_e32 v174, v175, v41
	v_rndne_f32_e32 v171, v171
	v_rndne_f32_e32 v172, v172
	v_rndne_f32_e32 v173, v173
	v_rndne_f32_e32 v174, v174
	v_med3_f32 v171, v171, s50, v186
	v_med3_f32 v172, v172, s50, v186
	v_med3_f32 v173, v173, s50, v186
	v_med3_f32 v174, v174, s50, v186
	v_cvt_i32_f32_e32 v171, v171
	v_cvt_i32_f32_e32 v172, v172
	v_cvt_i32_f32_e32 v173, v173
	v_cvt_i32_f32_e32 v174, v174
	v_and_b32_e32 v171, 0xff, v171
	v_and_b32_e32 v172, 0xff, v172
	v_and_b32_e32 v173, 0xff, v173
	v_lshl_or_b32 v171, v172, 8, v171
	v_lshl_or_b32 v171, v173, 16, v171
	v_lshl_or_b32 v208, v174, 24, v171
	v_lshlrev_b32_e32 v167, 16, v202
	v_and_b32_e32 v168, 0xffff0000, v202
	v_lshlrev_b32_e32 v169, 16, v203
	v_and_b32_e32 v170, 0xffff0000, v203
	v_add_f32_e32 v34, v34, v167
	v_add_f32_e32 v35, v35, v168
	v_add_f32_e32 v36, v36, v169
	v_add_f32_e32 v37, v37, v170
	v_cvt_pk_bf16_f32 v206, v34, v35
	v_cvt_pk_bf16_f32 v207, v36, v37
	v_mul_f32_e32 v171, v175, v34
	v_mul_f32_e32 v172, v175, v35
	v_mul_f32_e32 v173, v175, v36
	v_mul_f32_e32 v174, v175, v37
	v_rndne_f32_e32 v171, v171
	v_rndne_f32_e32 v172, v172
	v_rndne_f32_e32 v173, v173
	v_rndne_f32_e32 v174, v174
	v_med3_f32 v171, v171, s50, v186
	v_med3_f32 v172, v172, s50, v186
	v_med3_f32 v173, v173, s50, v186
	v_med3_f32 v174, v174, s50, v186
	v_cvt_i32_f32_e32 v171, v171
	v_cvt_i32_f32_e32 v172, v172
	v_cvt_i32_f32_e32 v173, v173
	v_cvt_i32_f32_e32 v174, v174
	v_and_b32_e32 v171, 0xff, v171
	v_and_b32_e32 v172, 0xff, v172
	v_and_b32_e32 v173, 0xff, v173
	v_lshl_or_b32 v171, v172, 8, v171
	v_lshl_or_b32 v171, v173, 16, v171
	v_lshl_or_b32 v209, v174, 24, v171
	global_store_dwordx4 v163, v[204:207], s[86:87] offset:256
	global_store_dwordx2 v164, v[208:209], s[88:89] offset:128
	s_nop 0
	s_add_u32 s86, s86, 0x20000
	s_addc_u32 s87, s87, 0
	s_add_u32 s88, s88, 0x10000
	s_addc_u32 s89, s89, 0
	global_load_dword v166, v162, s[28:29] offset:704
	global_load_dwordx4 v[196:199], v163, s[84:85]
	global_load_dwordx4 v[200:203], v163, s[84:85] offset:256
	s_waitcnt vmcnt(7)
; __device__ __forceinline__ u32x4 pack8(const f32x4 a, const f32x4 b) { u32x4 w; w.x = cvt_pk_bf16(a[0], a[1]); w.y = cvt_pk_bf16(a[2], a[3]); w.z = cvt_pk_bf16(b[0], b[1]); w.w = cvt_pk_bf16(b[2], b[3]); return w; }
;     __device__ __forceinline__ void operator()(const f32x4 (&acc)[2][2][4][2], const pg8::Unit& u, int wr, int wc, int fr, int fq) const {
;         const int row0 = u.pm * 256 + wr * 64 + fr, col0 = u.pn * 256 + wc * 32 + 8 * fq;
; #pragma unroll
;         for (int ai = 0; ai < 2; ++ai) {
;             u32x4 hr[4][2]; float q1v[4];
; #pragma unroll
;             for (int m = 0; m < 4; ++m) { q1v[m] = rss1[row0 + ai * 128 + m * 16];
; #pragma unroll
;                 for (int bj = 0; bj < 2; ++bj) hr[m][bj] = *(const u32x4*)(HB + (size_t)(row0 + ai * 128 + m * 16) * DM + col0 + bj * 128); }
; #pragma unroll
;             for (int m = 0; m < 4; ++m) { const float iq = (127.f / QCLIP) * rsqrtf(q1v[m] * (1.f / DM) + EPS);
; #pragma unroll
;                 for (int bj = 0; bj < 2; ++bj) { float hv[8]; unpack8(hr[m][bj], hv); const size_t off = (size_t)(row0 + ai * 128 + m * 16) * DM + col0 + bj * 128;
;                     f32x4 h0 = acc[ai][bj][m][0], h1 = acc[ai][bj][m][1];
; #pragma unroll
;                     for (int e = 0; e < 4; ++e) { h0[e] += hv[e]; h1[e] += hv[4 + e]; }
;                     *(u32x4*)(HB + off) = pack8(h0, h1);
;                     f32x4 q0, q1;
; #pragma unroll
;                     for (int ee = 0; ee < 4; ++ee) { q0[ee] = fminf(fmaxf(rintf(h0[ee] * iq), -127.f), 127.f); q1[ee] = fminf(fmaxf(rintf(h1[ee] * iq), -127.f), 127.f); }
;                     *(u32x2*)(HQ + off) = pack8_i8(q0, q1); } }
	v_fmamk_f32 v175, v165, 0x39800000, v185
	v_rsq_f32_e32 v175, v175
	s_nop 0
	v_mul_f32_e32 v175, 0x41e1c71c, v175
	v_lshlrev_b32_e32 v167, 16, v188
	v_and_b32_e32 v168, 0xffff0000, v188
	v_lshlrev_b32_e32 v169, 16, v189
	v_and_b32_e32 v170, 0xffff0000, v189
	v_add_f32_e32 v30, v30, v167
	v_add_f32_e32 v31, v31, v168
	v_add_f32_e32 v32, v32, v169
	v_add_f32_e32 v33, v33, v170
	v_cvt_pk_bf16_f32 v204, v30, v31
	v_cvt_pk_bf16_f32 v205, v32, v33
	v_mul_f32_e32 v171, v175, v30
	v_mul_f32_e32 v172, v175, v31
	v_mul_f32_e32 v173, v175, v32
	v_mul_f32_e32 v174, v175, v33
	v_rndne_f32_e32 v171, v171
	v_rndne_f32_e32 v172, v172
	v_rndne_f32_e32 v173, v173
	v_rndne_f32_e32 v174, v174
	v_med3_f32 v171, v171, s50, v186
	v_med3_f32 v172, v172, s50, v186
	v_med3_f32 v173, v173, s50, v186
	v_med3_f32 v174, v174, s50, v186
	v_cvt_i32_f32_e32 v171, v171
	v_cvt_i32_f32_e32 v172, v172
	v_cvt_i32_f32_e32 v173, v173
	v_cvt_i32_f32_e32 v174, v174
	v_and_b32_e32 v171, 0xff, v171
	v_and_b32_e32 v172, 0xff, v172
	v_and_b32_e32 v173, 0xff, v173
	v_lshl_or_b32 v171, v172, 8, v171
	v_lshl_or_b32 v171, v173, 16, v171
	v_lshl_or_b32 v208, v174, 24, v171
	v_lshlrev_b32_e32 v167, 16, v190
	v_and_b32_e32 v168, 0xffff0000, v190
	v_lshlrev_b32_e32 v169, 16, v191
	v_and_b32_e32 v170, 0xffff0000, v191
	v_add_f32_e32 v26, v26, v167
	v_add_f32_e32 v27, v27, v168
	v_add_f32_e32 v28, v28, v169
	v_add_f32_e32 v29, v29, v170
	v_cvt_pk_bf16_f32 v206, v26, v27
	v_cvt_pk_bf16_f32 v207, v28, v29
	v_mul_f32_e32 v171, v175, v26
	v_mul_f32_e32 v172, v175, v27
	v_mul_f32_e32 v173, v175, v28
	v_mul_f32_e32 v174, v175, v29
	v_rndne_f32_e32 v171, v171
	v_rndne_f32_e32 v172, v172
	v_rndne_f32_e32 v173, v173
	v_rndne_f32_e32 v174, v174
	v_med3_f32 v171, v171, s50, v186
	v_med3_f32 v172, v172, s50, v186
	v_med3_f32 v173, v173, s50, v186
	v_med3_f32 v174, v174, s50, v186
	v_cvt_i32_f32_e32 v171, v171
	v_cvt_i32_f32_e32 v172, v172
	v_cvt_i32_f32_e32 v173, v173
	v_cvt_i32_f32_e32 v174, v174
	v_and_b32_e32 v171, 0xff, v171
	v_and_b32_e32 v172, 0xff, v172
	v_and_b32_e32 v173, 0xff, v173
	v_lshl_or_b32 v171, v172, 8, v171
	v_lshl_or_b32 v171, v173, 16, v171
	v_lshl_or_b32 v209, v174, 24, v171
	global_store_dwordx4 v163, v[204:207], s[86:87]
	global_store_dwordx2 v164, v[208:209], s[88:89]
	s_nop 0
	v_lshlrev_b32_e32 v167, 16, v192
	v_and_b32_e32 v168, 0xffff0000, v192
	v_lshlrev_b32_e32 v169, 16, v193
	v_and_b32_e32 v170, 0xffff0000, v193
	v_add_f32_e32 v22, v22, v167
	v_add_f32_e32 v23, v23, v168
	v_add_f32_e32 v24, v24, v169
	v_add_f32_e32 v25, v25, v170
	v_cvt_pk_bf16_f32 v204, v22, v23
	v_cvt_pk_bf16_f32 v205, v24, v25
	v_mul_f32_e32 v171, v175, v22
	v_mul_f32_e32 v172, v175, v23
	v_mul_f32_e32 v173, v175, v24
	v_mul_f32_e32 v174, v175, v25
	v_rndne_f32_e32 v171, v171
	v_rndne_f32_e32 v172, v172
	v_rndne_f32_e32 v173, v173
	v_rndne_f32_e32 v174, v174
	v_med3_f32 v171, v171, s50, v186
	v_med3_f32 v172, v172, s50, v186
	v_med3_f32 v173, v173, s50, v186
	v_med3_f32 v174, v174, s50, v186
	v_cvt_i32_f32_e32 v171, v171
	v_cvt_i32_f32_e32 v172, v172
	v_cvt_i32_f32_e32 v173, v173
	v_cvt_i32_f32_e32 v174, v174
	v_and_b32_e32 v171, 0xff, v171
	v_and_b32_e32 v172, 0xff, v172
	v_and_b32_e32 v173, 0xff, v173
	v_lshl_or_b32 v171, v172, 8, v171
	v_lshl_or_b32 v171, v173, 16, v171
	v_lshl_or_b32 v208, v174, 24, v171
	v_lshlrev_b32_e32 v167, 16, v194
	v_and_b32_e32 v168, 0xffff0000, v194
	v_lshlrev_b32_e32 v169, 16, v195
	v_and_b32_e32 v170, 0xffff0000, v195
	v_add_f32_e32 v18, v18, v167
	v_add_f32_e32 v19, v19, v168
	v_add_f32_e32 v20, v20, v169
	v_add_f32_e32 v21, v21, v170
	v_cvt_pk_bf16_f32 v206, v18, v19
	v_cvt_pk_bf16_f32 v207, v20, v21
	v_mul_f32_e32 v171, v175, v18
	v_mul_f32_e32 v172, v175, v19
	v_mul_f32_e32 v173, v175, v20
	v_mul_f32_e32 v174, v175, v21
	v_rndne_f32_e32 v171, v171
	v_rndne_f32_e32 v172, v172
	v_rndne_f32_e32 v173, v173
	v_rndne_f32_e32 v174, v174
	v_med3_f32 v171, v171, s50, v186
	v_med3_f32 v172, v172, s50, v186
	v_med3_f32 v173, v173, s50, v186
	v_med3_f32 v174, v174, s50, v186
	v_cvt_i32_f32_e32 v171, v171
	v_cvt_i32_f32_e32 v172, v172
	v_cvt_i32_f32_e32 v173, v173
	v_cvt_i32_f32_e32 v174, v174
	v_and_b32_e32 v171, 0xff, v171
	v_and_b32_e32 v172, 0xff, v172
	v_and_b32_e32 v173, 0xff, v173
	v_lshl_or_b32 v171, v172, 8, v171
	v_lshl_or_b32 v171, v173, 16, v171
	v_lshl_or_b32 v209, v174, 24, v171
	global_store_dwordx4 v163, v[204:207], s[86:87] offset:256
	global_store_dwordx2 v164, v[208:209], s[88:89] offset:128
	s_nop 0
	s_add_u32 s86, s86, 0x20000
	s_addc_u32 s87, s87, 0
	s_add_u32 s88, s88, 0x10000
	s_addc_u32 s89, s89, 0
	s_waitcnt vmcnt(4)
; __device__ __forceinline__ u32x4 pack8(const f32x4 a, const f32x4 b) { u32x4 w; w.x = cvt_pk_bf16(a[0], a[1]); w.y = cvt_pk_bf16(a[2], a[3]); w.z = cvt_pk_bf16(b[0], b[1]); w.w = cvt_pk_bf16(b[2], b[3]); return w; }
;     __device__ __forceinline__ void operator()(const f32x4 (&acc)[2][2][4][2], const pg8::Unit& u, int wr, int wc, int fr, int fq) const {
;     ...
;             for (int m = 0; m < 4; ++m) { const float iq = (127.f / QCLIP) * rsqrtf(q1v[m] * (1.f / DM) + EPS);
; #pragma unroll
;                 for (int bj = 0; bj < 2; ++bj) { float hv[8]; unpack8(hr[m][bj], hv); const size_t off = (size_t)(row0 + ai * 128 + m * 16) * DM + col0 + bj * 128;
;                     f32x4 h0 = acc[ai][bj][m][0], h1 = acc[ai][bj][m][1];
; #pragma unroll
;                     for (int e = 0; e < 4; ++e) { h0[e] += hv[e]; h1[e] += hv[4 + e]; }
;                     *(u32x4*)(HB + off) = pack8(h0, h1);
;                     f32x4 q0, q1;
; #pragma unroll
;                     for (int ee = 0; ee < 4; ++ee) { q0[ee] = fminf(fmaxf(rintf(h0[ee] * iq), -127.f), 127.f); q1[ee] = fminf(fmaxf(rintf(h1[ee] * iq), -127.f), 127.f); }
;                     *(u32x2*)(HQ + off) = pack8_i8(q0, q1); } }
;             asm volatile("" ::: "memory"); }
	v_fmamk_f32 v175, v166, 0x39800000, v185
	v_rsq_f32_e32 v175, v175
	s_nop 0
	v_mul_f32_e32 v175, 0x41e1c71c, v175
	v_lshlrev_b32_e32 v167, 16, v196
	v_and_b32_e32 v168, 0xffff0000, v196
	v_lshlrev_b32_e32 v169, 16, v197
	v_and_b32_e32 v170, 0xffff0000, v197
	v_add_f32_e32 v14, v14, v167
	v_add_f32_e32 v15, v15, v168
	v_add_f32_e32 v16, v16, v169
	v_add_f32_e32 v17, v17, v170
	v_cvt_pk_bf16_f32 v204, v14, v15
	v_cvt_pk_bf16_f32 v205, v16, v17
	v_mul_f32_e32 v171, v175, v14
	v_mul_f32_e32 v172, v175, v15
	v_mul_f32_e32 v173, v175, v16
	v_mul_f32_e32 v174, v175, v17
	v_rndne_f32_e32 v171, v171
	v_rndne_f32_e32 v172, v172
	v_rndne_f32_e32 v173, v173
	v_rndne_f32_e32 v174, v174
	v_med3_f32 v171, v171, s50, v186
	v_med3_f32 v172, v172, s50, v186
	v_med3_f32 v173, v173, s50, v186
	v_med3_f32 v174, v174, s50, v186
	v_cvt_i32_f32_e32 v171, v171
	v_cvt_i32_f32_e32 v172, v172
	v_cvt_i32_f32_e32 v173, v173
	v_cvt_i32_f32_e32 v174, v174
	v_and_b32_e32 v171, 0xff, v171
	v_and_b32_e32 v172, 0xff, v172
	v_and_b32_e32 v173, 0xff, v173
	v_lshl_or_b32 v171, v172, 8, v171
	v_lshl_or_b32 v171, v173, 16, v171
	v_lshl_or_b32 v208, v174, 24, v171
	v_lshlrev_b32_e32 v167, 16, v198
	v_and_b32_e32 v168, 0xffff0000, v198
	v_lshlrev_b32_e32 v169, 16, v199
	v_and_b32_e32 v170, 0xffff0000, v199
	v_add_f32_e32 v10, v10, v167
	v_add_f32_e32 v11, v11, v168
	v_add_f32_e32 v12, v12, v169
	v_add_f32_e32 v13, v13, v170
	v_cvt_pk_bf16_f32 v206, v10, v11
	v_cvt_pk_bf16_f32 v207, v12, v13
	v_mul_f32_e32 v171, v175, v10
	v_mul_f32_e32 v172, v175, v11
	v_mul_f32_e32 v173, v175, v12
	v_mul_f32_e32 v174, v175, v13
	v_rndne_f32_e32 v171, v171
	v_rndne_f32_e32 v172, v172
	v_rndne_f32_e32 v173, v173
	v_rndne_f32_e32 v174, v174
	v_med3_f32 v171, v171, s50, v186
	v_med3_f32 v172, v172, s50, v186
	v_med3_f32 v173, v173, s50, v186
	v_med3_f32 v174, v174, s50, v186
	v_cvt_i32_f32_e32 v171, v171
	v_cvt_i32_f32_e32 v172, v172
	v_cvt_i32_f32_e32 v173, v173
	v_cvt_i32_f32_e32 v174, v174
	v_and_b32_e32 v171, 0xff, v171
	v_and_b32_e32 v172, 0xff, v172
	v_and_b32_e32 v173, 0xff, v173
	v_lshl_or_b32 v171, v172, 8, v171
	v_lshl_or_b32 v171, v173, 16, v171
	v_lshl_or_b32 v209, v174, 24, v171
	global_store_dwordx4 v163, v[204:207], s[86:87]
	global_store_dwordx2 v164, v[208:209], s[88:89]
	s_nop 0
	v_lshlrev_b32_e32 v167, 16, v200
	v_and_b32_e32 v168, 0xffff0000, v200
	v_lshlrev_b32_e32 v169, 16, v201
	v_and_b32_e32 v170, 0xffff0000, v201
	v_add_f32_e32 v6, v6, v167
	v_add_f32_e32 v7, v7, v168
	v_add_f32_e32 v8, v8, v169
	v_add_f32_e32 v9, v9, v170
	v_cvt_pk_bf16_f32 v204, v6, v7
	v_cvt_pk_bf16_f32 v205, v8, v9
	v_mul_f32_e32 v171, v175, v6
	v_mul_f32_e32 v172, v175, v7
	v_mul_f32_e32 v173, v175, v8
	v_mul_f32_e32 v174, v175, v9
	v_rndne_f32_e32 v171, v171
	v_rndne_f32_e32 v172, v172
	v_rndne_f32_e32 v173, v173
	v_rndne_f32_e32 v174, v174
	v_med3_f32 v171, v171, s50, v186
	v_med3_f32 v172, v172, s50, v186
	v_med3_f32 v173, v173, s50, v186
	v_med3_f32 v174, v174, s50, v186
	v_cvt_i32_f32_e32 v171, v171
	v_cvt_i32_f32_e32 v172, v172
	v_cvt_i32_f32_e32 v173, v173
	v_cvt_i32_f32_e32 v174, v174
	v_and_b32_e32 v171, 0xff, v171
	v_and_b32_e32 v172, 0xff, v172
	v_and_b32_e32 v173, 0xff, v173
	v_lshl_or_b32 v171, v172, 8, v171
	v_lshl_or_b32 v171, v173, 16, v171
	v_lshl_or_b32 v208, v174, 24, v171
	v_lshlrev_b32_e32 v167, 16, v202
	v_and_b32_e32 v168, 0xffff0000, v202
	v_lshlrev_b32_e32 v169, 16, v203
	v_and_b32_e32 v170, 0xffff0000, v203
	v_add_f32_e32 v2, v2, v167
	v_add_f32_e32 v3, v3, v168
	v_add_f32_e32 v4, v4, v169
	v_add_f32_e32 v5, v5, v170
	v_cvt_pk_bf16_f32 v206, v2, v3
	v_cvt_pk_bf16_f32 v207, v4, v5
	v_mul_f32_e32 v171, v175, v2
	v_mul_f32_e32 v172, v175, v3
	v_mul_f32_e32 v173, v175, v4
	v_mul_f32_e32 v174, v175, v5
	v_rndne_f32_e32 v171, v171
	v_rndne_f32_e32 v172, v172
	v_rndne_f32_e32 v173, v173
	v_rndne_f32_e32 v174, v174
	v_med3_f32 v171, v171, s50, v186
	v_med3_f32 v172, v172, s50, v186
	v_med3_f32 v173, v173, s50, v186
	v_med3_f32 v174, v174, s50, v186
	v_cvt_i32_f32_e32 v171, v171
	v_cvt_i32_f32_e32 v172, v172
	v_cvt_i32_f32_e32 v173, v173
	v_cvt_i32_f32_e32 v174, v174
	v_and_b32_e32 v171, 0xff, v171
	v_and_b32_e32 v172, 0xff, v172
	v_and_b32_e32 v173, 0xff, v173
	v_lshl_or_b32 v171, v172, 8, v171
	v_lshl_or_b32 v171, v173, 16, v171
	v_lshl_or_b32 v209, v174, 24, v171
	global_store_dwordx4 v163, v[204:207], s[86:87] offset:256
	global_store_dwordx2 v164, v[208:209], s[88:89] offset:128
	s_nop 0
	s_nop 1
	s_and_b64 vcc, exec, s[6:7]
	s_mov_b64 s[6:7], -1
	s_cbranch_vccnz .LBB0_1364
	s_andn2_b64 vcc, exec, s[12:13]
	s_cbranch_vccnz .LBB0_1363
	s_barrier
	s_branch .LBB0_1363
